# MLA attention loop rescheduled: S0 chain first, S1 tail under softmax0, V frag reads before LDS stores, LDS stores+prefetch moved under PV1, barrier at tile end
# speedup vs baseline: 1.0056x; 1.0056x over previous
; template <int DQK, bool ALIBI>
; DI void attn_pass(const u16* __restrict__ Qp, int ldq, const u16* __restrict__ Kp, int ldk, const u16* __restrict__ VTp,
;                   int seq_start, int kt_lo, int kt_hi, int q0, float slope2, f32x16 (&O)[4], float& lsum, char* lds) {
;     ...
;       if (kb + 64 <= qw0 || kb > qw0 + 31) {
;         const float sl = (kb + 64 <= qw0) ? slope2 : -slope2;
;         const float T0 = -sl * dq, T1 = T0 + 32.f * sl;
; #pragma unroll
;         for (int i = 0; i < 16; ++i) {
;           S0[i] = fmaf(sl, (float)((i & 3) + 8 * (i >> 2)), T0);
;           S1[i] = fmaf(sl, (float)((i & 3) + 8 * (i >> 2)), T1);
;         }
.LBB0_1151:
	s_andn2_saveexec_b64 s[6:7], s[6:7]
	s_cbranch_execz .LBB0_1153
	v_cndmask_b32_e64 v145, -v149, v149, vcc
	v_xor_b32_e32 v192, 0x80000000, v145
	v_pk_mul_f32 v[80:81], v[144:145], v[192:193]
	s_nop 0
	v_pk_fma_f32 v[160:161], v[144:145], v[192:193], v[80:81] op_sel:[0,0,1] op_sel_hi:[1,1,0]
	v_mov_b32_e32 v144, v145
	v_fma_f32 v82, 0, v145, v80
	v_fma_f32 v66, 0, v145, v160
	v_add_f32_e32 v83, v145, v80
	v_add_f32_e32 v67, v145, v160
	v_pk_fma_f32 v[84:85], v[144:145], s[20:21], v[80:81] op_sel_hi:[0,1,0]
	v_pk_fma_f32 v[68:69], v[144:145], s[20:21], v[160:161] op_sel_hi:[0,1,0]
	v_pk_fma_f32 v[86:87], v[144:145], s[8:9], v[80:81] op_sel_hi:[0,1,0]
	v_pk_fma_f32 v[70:71], v[144:145], s[8:9], v[160:161] op_sel_hi:[0,1,0]
	v_pk_fma_f32 v[88:89], v[144:145], s[26:27], v[80:81] op_sel_hi:[0,1,0]
	v_pk_fma_f32 v[72:73], v[144:145], s[26:27], v[160:161] op_sel_hi:[0,1,0]
	v_pk_fma_f32 v[90:91], v[144:145], s[28:29], v[80:81] op_sel_hi:[0,1,0]
	v_pk_fma_f32 v[74:75], v[144:145], s[28:29], v[160:161] op_sel_hi:[0,1,0]
	v_pk_fma_f32 v[92:93], v[144:145], s[30:31], v[80:81] op_sel_hi:[0,1,0]
	v_pk_fma_f32 v[76:77], v[144:145], s[30:31], v[160:161] op_sel_hi:[0,1,0]
	v_pk_fma_f32 v[94:95], v[144:145], s[36:37], v[80:81] op_sel_hi:[0,1,0]
	v_pk_fma_f32 v[78:79], v[144:145], s[36:37], v[160:161] op_sel_hi:[0,1,0]
	v_pk_fma_f32 v[96:97], v[144:145], s[78:79], v[80:81] op_sel_hi:[0,1,0]
	v_pk_fma_f32 v[80:81], v[144:145], s[78:79], v[160:161] op_sel_hi:[0,1,0]

; #define MFMA(a, b, c) __builtin_amdgcn_mfma_f32_32x32x16_bf16((a), (b), (c), 0, 0, 0)
; template <int DQK, bool ALIBI>
; DI void attn_pass(const u16* __restrict__ Qp, int ldq, const u16* __restrict__ Kp, int ldk, const u16* __restrict__ VTp,
;                   int seq_start, int kt_lo, int kt_hi, int q0, float slope2, f32x16 (&O)[4], float& lsum, char* lds) {
;     ...
; #pragma unroll
;     for (int s = 0; s < 2; ++s)
; #pragma unroll
;       for (int db = 0; db < 4; ++db) vf[s][db] = *(const bf16x8*)(Vs + (db * 32 + r) * 72 + s * 16 + h * 8);
;     __builtin_amdgcn_sched_barrier(0);
;     bf16x8 pf[2];
;     ...
;     ATT_SOFTMAX(S0);
;     __builtin_amdgcn_sched_barrier(0);
; #pragma unroll
;     for (int s = 0; s < 2; ++s)
; #pragma unroll
;       for (int db = 0; db < 4; ++db) O[db] = MFMA(vf[s][db], pf[s], O[db]);
;     bf16x8 vg[2][4];
; #pragma unroll
;     for (int s = 0; s < 2; ++s)
; #pragma unroll
;       for (int db = 0; db < 4; ++db) vg[s][db] = *(const bf16x8*)(Vs + (db * 32 + r) * 72 + 32 + s * 16 + h * 8);
;     bf16x8 pg[2];
;     {
;       float pv[16];
; #pragma unroll
;       for (int i = 0; i < 16; ++i) pv[i] = __builtin_amdgcn_exp2f(S1[i]);
; #pragma unroll
;       for (int i = 0; i < 8; ++i) l2 += f32x2{pv[2 * i], pv[2 * i + 1]};
; #pragma unroll
;       for (int s = 0; s < 2; ++s) {
;         u32 a0 = pack2(pv[8 * s], pv[8 * s + 1]), a1 = pack2(pv[8 * s + 2], pv[8 * s + 3]);
;         u32 a2 = pack2(pv[8 * s + 4], pv[8 * s + 5]), a3 = pack2(pv[8 * s + 6], pv[8 * s + 7]);
;         u32x4 pk = {a0, a1, a2, a3};
;         pg[s] = __builtin_bit_cast(bf16x8, pk);
;       }
;     }
; #pragma unroll
;     for (int g = 0; g < 8; ++g) {
;       __builtin_amdgcn_sched_group_barrier(0x008, 1, 0);
;       __builtin_amdgcn_sched_group_barrier(0x100, 1, 0);
;       __builtin_amdgcn_sched_group_barrier(0x002, 5, 0);
;     }
;     __builtin_amdgcn_sched_barrier(0);
; #pragma unroll
;     for (int s = 0; s < 2; ++s)
; #pragma unroll
;       for (int db = 0; db < 4; ++db) O[db] = MFMA(vg[s][db], pg[s], O[db]);
;     __syncthreads();
.LBB0_1161:
	v_add3_u32 v144, s44, v0, v156
	ds_read_b128 v[160:163], v144 offset:9216
	ds_read_b128 v[164:167], v144 offset:9248
	ds_read_b128 v[168:171], v144 offset:13824
	ds_read_b128 v[172:175], v144 offset:13856
	ds_read_b128 v[176:179], v144 offset:18432
	ds_read_b128 v[180:183], v144 offset:18464
	ds_read_b128 v[184:187], v144 offset:23040
	ds_read_b128 v[194:197], v144 offset:23072
	v_exp_f32_e32 v144, v82
	v_exp_f32_e32 v145, v83
	v_exp_f32_e32 v198, v84
	v_exp_f32_e32 v199, v85
	v_exp_f32_e32 v200, v86
	v_exp_f32_e32 v201, v87
	v_exp_f32_e32 v202, v88
	v_exp_f32_e32 v203, v89
	v_exp_f32_e32 v90, v90
	v_exp_f32_e32 v91, v91
	v_exp_f32_e32 v204, v96
	v_exp_f32_e32 v205, v97
	v_pk_add_f32 v[96:97], v[142:143], v[144:145]
	v_exp_f32_e32 v92, v92
	v_exp_f32_e32 v93, v93
	v_pk_add_f32 v[96:97], v[198:199], v[96:97]
	v_exp_f32_e32 v94, v94
	v_exp_f32_e32 v95, v95
	v_pk_add_f32 v[96:97], v[200:201], v[96:97]
	v_cvt_pk_bf16_f32 v86, v90, v91
	v_pk_add_f32 v[96:97], v[202:203], v[96:97]
	v_cvt_pk_bf16_f32 v82, v144, v145
	v_pk_add_f32 v[90:91], v[90:91], v[96:97]
	v_cvt_pk_bf16_f32 v83, v198, v199
	v_pk_add_f32 v[90:91], v[92:93], v[90:91]
	v_cvt_pk_bf16_f32 v84, v200, v201
	v_cvt_pk_bf16_f32 v85, v202, v203
	v_cvt_pk_bf16_f32 v87, v92, v93
	v_cvt_pk_bf16_f32 v88, v94, v95
	v_cvt_pk_bf16_f32 v89, v204, v205
	v_pk_add_f32 v[198:199], v[94:95], v[90:91]
	s_waitcnt lgkmcnt(7)
	v_mfma_f32_32x32x16_bf16 v[50:65], v[160:163], v[82:85], v[50:65]
	v_exp_f32_e32 v74, v74
	v_exp_f32_e32 v75, v75
	v_exp_f32_e32 v76, v76
	v_exp_f32_e32 v77, v77
	v_exp_f32_e32 v78, v78
	v_exp_f32_e32 v79, v79
	v_exp_f32_e32 v80, v80
	s_waitcnt lgkmcnt(5)
	v_mfma_f32_32x32x16_bf16 v[34:49], v[168:171], v[82:85], v[34:49]
	v_exp_f32_e32 v81, v81
	s_waitcnt lgkmcnt(3)
	v_mfma_f32_32x32x16_bf16 v[18:33], v[176:179], v[82:85], v[18:33]
	v_exp_f32_e32 v176, v70
	v_exp_f32_e32 v177, v71
	v_exp_f32_e32 v178, v72
	v_exp_f32_e32 v179, v73
	s_waitcnt lgkmcnt(1)
	v_mfma_f32_32x32x16_bf16 v[2:17], v[184:187], v[82:85], v[2:17]
	v_add_u32_e32 v82, v131, v0
	ds_read_b128 v[168:171], v82 offset:18528
	v_mfma_f32_32x32x16_bf16 v[50:65], v[164:167], v[86:89], v[50:65]
	ds_read_b128 v[164:167], v82 offset:13920
	ds_read_b128 v[160:163], v82 offset:9312
	ds_read_b128 v[90:93], v82 offset:18496
	v_mfma_f32_32x32x16_bf16 v[34:49], v[172:175], v[86:89], v[34:49]
	v_exp_f32_e32 v172, v66
	v_exp_f32_e32 v173, v67
	v_exp_f32_e32 v174, v68
	v_exp_f32_e32 v175, v69
	ds_read_b128 v[94:97], v82 offset:23104
	v_mfma_f32_32x32x16_bf16 v[18:33], v[180:183], v[86:89], v[18:33]
	ds_read_b128 v[142:145], v82 offset:9280
	s_waitcnt lgkmcnt(6)
	v_mfma_f32_32x32x16_bf16 v[2:17], v[194:197], v[86:89], v[2:17]
	ds_read_b128 v[86:89], v82 offset:13888
	ds_read_b128 v[82:85], v82 offset:23136
	v_add_f32_e64 v180, v204, v198
	v_add_f32_e64 v181, v205, v199
	v_cvt_pk_bf16_f32 v66, v172, v173
	v_pk_add_f32 v[172:173], v[172:173], v[180:181]
	s_nop 0
	v_pk_add_f32 v[172:173], v[174:175], v[172:173]
	s_nop 0
	v_pk_add_f32 v[172:173], v[176:177], v[172:173]
	s_nop 0
	v_pk_add_f32 v[172:173], v[178:179], v[172:173]
	v_cvt_pk_bf16_f32 v70, v74, v75
	v_pk_add_f32 v[74:75], v[74:75], v[172:173]
	s_nop 0
	v_pk_add_f32 v[74:75], v[76:77], v[74:75]
	s_nop 0
	v_pk_add_f32 v[74:75], v[78:79], v[74:75]
	v_cvt_pk_bf16_f32 v71, v76, v77
	v_cvt_pk_bf16_f32 v72, v78, v79
	v_cvt_pk_bf16_f32 v73, v80, v81
	v_cvt_pk_bf16_f32 v67, v174, v175
	v_cvt_pk_bf16_f32 v68, v176, v177
	v_cvt_pk_bf16_f32 v69, v178, v179
	s_waitcnt lgkmcnt(2)
	s_nop 0
	v_mfma_f32_32x32x16_bf16 v[50:65], v[142:145], v[66:69], v[50:65]
	s_add_i32 s87, s87, 1
	s_add_i32 s6, s73, s87
	v_add_f32_e64 v142, v80, v74
	v_add_f32_e64 v143, v81, v75
	v_lshl_add_u64 v[138:139], v[138:139], 0, s[80:81]
	v_lshl_add_u64 v[140:141], v[140:141], 0, s[80:81]
	s_cmp_lt_i32 s6, s77
	s_waitcnt lgkmcnt(0)
	v_mfma_f32_32x32x16_bf16 v[34:49], v[86:89], v[66:69], v[34:49]
	s_barrier
	v_mfma_f32_32x32x16_bf16 v[18:33], v[90:93], v[66:69], v[18:33]
	v_mfma_f32_32x32x16_bf16 v[2:17], v[94:97], v[66:69], v[2:17]
	v_mfma_f32_32x32x16_bf16 v[50:65], v[160:163], v[70:73], v[50:65]
	v_mfma_f32_32x32x16_bf16 v[34:49], v[164:167], v[70:73], v[34:49]
	v_mfma_f32_32x32x16_bf16 v[18:33], v[168:171], v[70:73], v[18:33]
	v_mfma_f32_32x32x16_bf16 v[2:17], v[82:85], v[70:73], v[2:17]
	s_cbranch_scc0 .LBB0_1163
	s_mov_b32 s89, s88
	s_branch .LBB0_1149

; #define MFMA(a, b, c) __builtin_amdgcn_mfma_f32_32x32x16_bf16((a), (b), (c), 0, 0, 0)
; template <int DQK, bool ALIBI>
; DI void attn_pass(const u16* __restrict__ Qp, int ldq, const u16* __restrict__ Kp, int ldk, const u16* __restrict__ VTp,
;                   int seq_start, int kt_lo, int kt_hi, int q0, float slope2, f32x16 (&O)[4], float& lsum, char* lds) {
;     ...
;     for (int ks = 0; ks < NKS; ++ks) {
;       k0[ks] = *(const bf16x8*)(Ks + r * KST + ks * 16 + h * 8);
;       k1[ks] = *(const bf16x8*)(Ks + (32 + r) * KST + ks * 16 + h * 8);
;     }
;     __builtin_amdgcn_sched_barrier(0);
; #pragma unroll
;     for (int ks = 0; ks < NKS; ++ks) {
;       S0 = MFMA(k0[ks], qf[ks], S0);
;       S1 = MFMA(k1[ks], qf[ks], S1);
;     }
;     if (kt + 1 < kt_hi) ATT_LSTORE(cur ^ 1);
;     if (kt + 2 < kt_hi) ATT_GLOAD(kt + 2);
; #pragma unroll
;     for (int s = 0; s < 2; ++s)
; #pragma unroll
;       for (int db = 0; db < 4; ++db) vf[s][db] = *(const bf16x8*)(Vs + (db * 32 + r) * 72 + s * 16 + h * 8);
;     __builtin_amdgcn_sched_barrier(0);
;     bf16x8 pf[2];
;     ...
;     ATT_SOFTMAX(S0);
;     __builtin_amdgcn_sched_barrier(0);
; #pragma unroll
;     for (int s = 0; s < 2; ++s)
; #pragma unroll
;       for (int db = 0; db < 4; ++db) O[db] = MFMA(vf[s][db], pf[s], O[db]);
;     bf16x8 vg[2][4];
; #pragma unroll
;     for (int s = 0; s < 2; ++s)
; #pragma unroll
;       for (int db = 0; db < 4; ++db) vg[s][db] = *(const bf16x8*)(Vs + (db * 32 + r) * 72 + 32 + s * 16 + h * 8);
;     bf16x8 pg[2];
;     {
;       float pv[16];
; #pragma unroll
;       for (int i = 0; i < 16; ++i) pv[i] = __builtin_amdgcn_exp2f(S1[i]);
; #pragma unroll
;       for (int i = 0; i < 8; ++i) l2 += f32x2{pv[2 * i], pv[2 * i + 1]};
; #pragma unroll
;       for (int s = 0; s < 2; ++s) {
;         u32 a0 = pack2(pv[8 * s], pv[8 * s + 1]), a1 = pack2(pv[8 * s + 2], pv[8 * s + 3]);
;         u32 a2 = pack2(pv[8 * s + 4], pv[8 * s + 5]), a3 = pack2(pv[8 * s + 6], pv[8 * s + 7]);
;         u32x4 pk = {a0, a1, a2, a3};
;         pg[s] = __builtin_bit_cast(bf16x8, pk);
;       }
;     }
.LBB0_1193:
	s_add_i32 s44, s49, -2
	s_and_b32 s44, s44, 1
	s_mul_i32 s50, s44, 0x7c00
	v_add3_u32 v74, s50, v154, v161
	ds_read_b128 v[66:69], v74
	ds_read_b128 v[162:165], v74 offset:32
	ds_read_b128 v[170:173], v74 offset:64
	ds_read_b128 v[174:177], v74 offset:96
	ds_read_b128 v[194:197], v74 offset:128
	ds_read_b128 v[198:201], v74 offset:160
	ds_read_b128 v[70:73], v74 offset:6656
	ds_read_b128 v[166:169], v74 offset:6688
	ds_read_b128 v[178:181], v74 offset:6720
	ds_read_b128 v[182:185], v74 offset:6752
	ds_read_b128 v[202:205], v74 offset:6784
	ds_read_b128 v[234:237], v74 offset:6816
	s_xor_b32 s51, s44, 1
	s_mulk_i32 s51, 0x7c00
	s_waitcnt lgkmcnt(11)
	v_mfma_f32_32x32x16_bf16 v[82:97], v[66:69], v[118:121], 0
	s_waitcnt lgkmcnt(10)
	v_mfma_f32_32x32x16_bf16 v[82:97], v[162:165], v[114:117], v[82:97]
	s_waitcnt lgkmcnt(9)
	v_mfma_f32_32x32x16_bf16 v[82:97], v[170:173], v[110:113], v[82:97]
	s_waitcnt lgkmcnt(8)
	v_mfma_f32_32x32x16_bf16 v[82:97], v[174:177], v[106:109], v[82:97]
	s_waitcnt lgkmcnt(7)
	v_mfma_f32_32x32x16_bf16 v[82:97], v[194:197], v[102:105], v[82:97]
	s_waitcnt lgkmcnt(6)
	v_mfma_f32_32x32x16_bf16 v[82:97], v[198:201], v[98:101], v[82:97]
	s_waitcnt lgkmcnt(5)
	v_mfma_f32_32x32x16_bf16 v[66:81], v[70:73], v[118:121], 0
	s_waitcnt lgkmcnt(4)
	v_mfma_f32_32x32x16_bf16 v[66:81], v[166:169], v[114:117], v[66:81]
	v_add3_u32 v186, s50, v0, v151
	ds_read_b128 v[162:165], v186 offset:13312
	ds_read_b128 v[166:169], v186 offset:13344
	ds_read_b128 v[170:173], v186 offset:17920
	ds_read_b128 v[174:177], v186 offset:17952
	ds_read_b128 v[194:197], v186 offset:27136
	ds_read_b128 v[198:201], v186 offset:27168
	s_waitcnt lgkmcnt(8)
	v_mfma_f32_32x32x16_bf16 v[66:81], v[178:181], v[110:113], v[66:81]
	s_waitcnt lgkmcnt(7)
	v_mfma_f32_32x32x16_bf16 v[66:81], v[182:185], v[106:109], v[66:81]
	ds_read_b128 v[178:181], v186 offset:22528
	ds_read_b128 v[182:185], v186 offset:22560
	v_exp_f32_e32 v82, v82
	v_exp_f32_e32 v83, v83
	v_exp_f32_e32 v84, v84
	v_exp_f32_e32 v85, v85
	s_waitcnt lgkmcnt(9)
	v_mfma_f32_32x32x16_bf16 v[66:81], v[202:205], v[102:105], v[66:81]
	v_exp_f32_e32 v86, v86
	v_exp_f32_e32 v87, v87
	v_exp_f32_e32 v88, v88
	v_exp_f32_e32 v89, v89
	s_waitcnt lgkmcnt(8)
	v_mfma_f32_32x32x16_bf16 v[66:81], v[234:237], v[98:101], v[66:81]
	v_exp_f32_e32 v90, v90
	v_exp_f32_e32 v91, v91
	v_exp_f32_e32 v92, v92
	v_exp_f32_e32 v93, v93
	v_exp_f32_e32 v94, v94
	v_exp_f32_e32 v95, v95
	v_exp_f32_e32 v96, v96
	v_exp_f32_e32 v97, v97
	v_add_f32_e32 v148, v148, v82
	v_add_f32_e32 v149, v149, v83
	v_add_f32_e32 v148, v84, v148
	v_add_f32_e32 v149, v85, v149
	v_add_f32_e32 v148, v86, v148
	v_add_f32_e32 v149, v87, v149
	v_add_f32_e32 v148, v88, v148
	v_add_f32_e32 v149, v89, v149
	v_add_f32_e32 v148, v90, v148
	v_add_f32_e32 v149, v91, v149
	v_add_f32_e32 v148, v92, v148
	v_add_f32_e32 v149, v93, v149
	v_add_f32_e32 v148, v94, v148
	v_add_f32_e32 v149, v95, v149
	v_add_f32_e32 v148, v96, v148
	v_add_f32_e32 v149, v97, v149
	v_cvt_pk_bf16_f32 v82, v82, v83
	v_cvt_pk_bf16_f32 v83, v84, v85
	v_cvt_pk_bf16_f32 v84, v86, v87
	v_cvt_pk_bf16_f32 v85, v88, v89
	v_cvt_pk_bf16_f32 v86, v90, v91
	v_cvt_pk_bf16_f32 v87, v92, v93
	v_cvt_pk_bf16_f32 v88, v94, v95
	v_cvt_pk_bf16_f32 v89, v96, v97
	s_waitcnt lgkmcnt(7)
	v_mfma_f32_32x32x16_bf16 v[50:65], v[162:165], v[82:85], v[50:65]
	v_exp_f32_e32 v66, v66
	v_exp_f32_e32 v67, v67
	v_exp_f32_e32 v68, v68
	v_exp_f32_e32 v69, v69
	s_waitcnt lgkmcnt(5)
	v_mfma_f32_32x32x16_bf16 v[34:49], v[170:173], v[82:85], v[34:49]
	v_exp_f32_e32 v70, v70
	v_exp_f32_e32 v71, v71
	v_exp_f32_e32 v72, v72
	v_exp_f32_e32 v73, v73
	s_waitcnt lgkmcnt(3)
	v_mfma_f32_32x32x16_bf16 v[2:17], v[194:197], v[82:85], v[2:17]
	v_exp_f32_e32 v74, v74
	v_exp_f32_e32 v75, v75
	v_exp_f32_e32 v76, v76
	v_exp_f32_e32 v77, v77
	v_mfma_f32_32x32x16_bf16 v[34:49], v[174:177], v[86:89], v[34:49]
	ds_read_b128 v[174:177], v186 offset:22624
	ds_read_b128 v[170:173], v186 offset:18016
	v_exp_f32_e32 v78, v78
	v_exp_f32_e32 v79, v79
	v_exp_f32_e32 v80, v80
	v_exp_f32_e32 v81, v81
	v_mfma_f32_32x32x16_bf16 v[50:65], v[166:169], v[86:89], v[50:65]
	ds_read_b128 v[166:169], v186 offset:13408
	ds_read_b128 v[90:93], v186 offset:22592
	ds_read_b128 v[94:97], v186 offset:27200
	v_add_f32_e32 v148, v66, v148
	v_add_f32_e32 v149, v67, v149
	v_add_f32_e32 v148, v68, v148
	v_add_f32_e32 v149, v69, v149
	s_waitcnt lgkmcnt(7)
	v_mfma_f32_32x32x16_bf16 v[2:17], v[198:201], v[86:89], v[2:17]
	ds_read_b128 v[162:165], v186 offset:13376
	v_add_f32_e32 v148, v70, v148
	v_add_f32_e32 v149, v71, v149
	v_add_f32_e32 v148, v72, v148
	v_add_f32_e32 v149, v73, v149
	s_waitcnt lgkmcnt(7)
	v_mfma_f32_32x32x16_bf16 v[18:33], v[178:181], v[82:85], v[18:33]
	v_add_f32_e32 v148, v74, v148
	v_add_f32_e32 v149, v75, v149
	v_add_f32_e32 v148, v76, v148
	v_add_f32_e32 v149, v77, v149
	s_waitcnt lgkmcnt(6)
	v_mfma_f32_32x32x16_bf16 v[18:33], v[182:185], v[86:89], v[18:33]
	ds_read_b128 v[86:89], v186 offset:17984
	ds_read_b128 v[82:85], v186 offset:27232
	v_add_f32_e32 v148, v78, v148
	v_add_f32_e32 v149, v79, v149
	v_add_f32_e32 v148, v80, v148
	v_add_f32_e32 v149, v81, v149
	v_cvt_pk_bf16_f32 v66, v66, v67
	v_cvt_pk_bf16_f32 v67, v68, v69
	v_cvt_pk_bf16_f32 v68, v70, v71
	v_cvt_pk_bf16_f32 v69, v72, v73
	v_cvt_pk_bf16_f32 v70, v74, v75
	v_cvt_pk_bf16_f32 v71, v76, v77
	v_cvt_pk_bf16_f32 v72, v78, v79
	v_cvt_pk_bf16_f32 v73, v80, v81
	s_and_saveexec_b64 s[44:45], vcc
	s_cbranch_execz .LBB0_1195
	v_add3_u32 v186, s51, v155, v156
	s_waitcnt vmcnt(2)
	ds_write_b128 v186, v[122:125]
; #define MFMA(a, b, c) __builtin_amdgcn_mfma_f32_32x32x16_bf16((a), (b), (c), 0, 0, 0)
; template <int DQK, bool ALIBI>
; DI void attn_pass(const u16* __restrict__ Qp, int ldq, const u16* __restrict__ Kp, int ldk, const u16* __restrict__ VTp,
;                   int seq_start, int kt_lo, int kt_hi, int q0, float slope2, f32x16 (&O)[4], float& lsum, char* lds) {
;     ...
; #pragma unroll
;     for (int s = 0; s < 2; ++s)
; #pragma unroll
;       for (int db = 0; db < 4; ++db) O[db] = MFMA(vg[s][db], pg[s], O[db]);
;     __syncthreads();
.LBB0_1195:
	s_or_b64 exec, exec, s[44:45]
	s_and_saveexec_b64 s[44:45], s[42:43]
	s_cbranch_execz .LBB0_1197
	v_add3_u32 v186, s51, v157, v158
	s_waitcnt vmcnt(2)
	ds_write_b128 v186, v[126:129]
.LBB0_1197:
	s_or_b64 exec, exec, s[44:45]
	v_lshl_add_u32 v186, v139, 1, s51
	v_add_u32_e32 v187, v186, v152
	v_add_u32_e32 v186, v186, v153
	s_cmp_ge_u32 s49, s66
	s_waitcnt vmcnt(1)
	ds_write_b128 v187, v[130:133] offset:13312
	s_waitcnt vmcnt(0)
	ds_write_b128 v186, v[134:137] offset:13312
	s_cbranch_scc1 .Lmy_mla_pv1
	s_and_saveexec_b64 s[44:45], vcc
	s_cbranch_execz .LBB0_1200
	v_add_u32_e32 v122, s68, v159
	v_mad_i64_i32 v[122:123], s[52:53], v122, s77, v[140:141]
	global_load_dwordx4 v[122:125], v[122:123], off
.LBB0_1200:
	s_or_b64 exec, exec, s[44:45]
	s_and_saveexec_b64 s[44:45], s[42:43]
	s_cbranch_execz .LBB0_1191
	v_add_u32_e32 v126, s68, v160
	v_mad_i64_i32 v[126:127], s[52:53], v126, s77, v[142:143]
	global_load_dwordx4 v[126:129], v[126:127], off
.LBB0_1191:
	s_or_b64 exec, exec, s[44:45]
	global_load_dwordx4 v[130:133], v[146:147], off
	global_load_dwordx4 v[134:137], v[144:145], off
.Lmy_mla_pv1:
	s_waitcnt lgkmcnt(4)
	v_mfma_f32_32x32x16_bf16 v[50:65], v[162:165], v[66:69], v[50:65]
	s_add_i32 s49, s49, 1
	s_add_i32 s44, s48, s49
	s_add_i32 s68, s68, 64
	v_lshl_add_u64 v[144:145], v[144:145], 0, s[80:81]
	v_lshl_add_u64 v[146:147], v[146:147], 0, s[80:81]
	s_cmp_lg_u32 s44, 2
	s_waitcnt lgkmcnt(3)
	v_mfma_f32_32x32x16_bf16 v[34:49], v[86:89], v[66:69], v[34:49]
	v_mfma_f32_32x32x16_bf16 v[18:33], v[90:93], v[66:69], v[18:33]
	v_mfma_f32_32x32x16_bf16 v[2:17], v[94:97], v[66:69], v[2:17]
	v_mfma_f32_32x32x16_bf16 v[50:65], v[166:169], v[70:73], v[50:65]
	v_mfma_f32_32x32x16_bf16 v[34:49], v[170:173], v[70:73], v[34:49]
	v_mfma_f32_32x32x16_bf16 v[18:33], v[174:177], v[70:73], v[18:33]
	s_waitcnt lgkmcnt(2)
	v_mfma_f32_32x32x16_bf16 v[2:17], v[82:85], v[70:73], v[2:17]
	s_waitcnt lgkmcnt(0)
	s_barrier
	s_cbranch_scc0 .LBB0_1170
	s_branch .LBB0_1193
